# forget-prompt PV V-fragment reads through a 3-buffer ring (depth 6 was slower)
# baseline (speedup 1.0000x reference)
.LBB0_492:
	v_exp_f32_e32 v2, v114
	v_exp_f32_e32 v3, v115
	v_exp_f32_e32 v8, v118
	v_exp_f32_e32 v9, v119
	v_exp_f32_e32 v10, v120
	v_exp_f32_e32 v11, v121
	v_add_u32_e32 v12, s78, v239
	v_cvt_pk_bf16_f32 v6, v2, v3
	v_add3_u32 v2, v12, v240, v241
	v_exp_f32_e32 v5, v116
	v_exp_f32_e32 v7, v117
	v_cvt_pk_bf16_f32 v8, v8, v9
	v_cvt_pk_bf16_f32 v9, v10, v11
	ds_read_b64_tr_b16 v[182:183], v2 offset:22528
	ds_read_b64_tr_b16 v[184:185], v2 offset:23680
	ds_read_b64_tr_b16 v[186:187], v2 offset:22592
	ds_read_b64_tr_b16 v[188:189], v2 offset:23744
	ds_read_b64_tr_b16 v[10:11], v2 offset:24832
	ds_read_b64_tr_b16 v[12:13], v2 offset:25984
	v_cvt_pk_bf16_f32 v7, v5, v7
	v_exp_f32_e32 v14, v122
	v_exp_f32_e32 v15, v123
	s_waitcnt lgkmcnt(4)
	v_mfma_f32_32x32x16_bf16 v[34:49], v[182:185], v[6:9], v[34:49]
	ds_read_b64_tr_b16 v[182:183], v2 offset:24896
	ds_read_b64_tr_b16 v[184:185], v2 offset:26048
	v_exp_f32_e32 v16, v124
	v_exp_f32_e32 v17, v125
	v_exp_f32_e32 v114, v126
	v_exp_f32_e32 v115, v127
	v_exp_f32_e32 v116, v128
	v_exp_f32_e32 v117, v129
	s_waitcnt lgkmcnt(4)
	v_mfma_f32_32x32x16_bf16 v[18:33], v[186:189], v[6:9], v[18:33]
	ds_read_b64_tr_b16 v[186:187], v2 offset:27136
	ds_read_b64_tr_b16 v[188:189], v2 offset:28288
	v_exp_f32_e32 v82, v82
	v_exp_f32_e32 v83, v83
	v_exp_f32_e32 v84, v84
	v_exp_f32_e32 v85, v85
	v_exp_f32_e32 v86, v86
	v_exp_f32_e32 v87, v87
	v_mfma_f32_32x32x16_bf16 v[50:65], v[134:137], v[6:9], v[50:65]
	v_cvt_pk_bf16_f32 v6, v14, v15
	v_cvt_pk_bf16_f32 v7, v16, v17
	v_cvt_pk_bf16_f32 v8, v114, v115
	v_cvt_pk_bf16_f32 v9, v116, v117
	v_exp_f32_e32 v88, v88
	v_exp_f32_e32 v89, v89
	v_exp_f32_e32 v90, v90
	s_waitcnt lgkmcnt(4)
	v_mfma_f32_32x32x16_bf16 v[34:49], v[10:13], v[6:9], v[34:49]
	ds_read_b64_tr_b16 v[10:11], v2 offset:27200
	ds_read_b64_tr_b16 v[12:13], v2 offset:28352
	v_exp_f32_e32 v91, v91
	v_exp_f32_e32 v92, v92
	v_exp_f32_e32 v93, v93
	v_exp_f32_e32 v94, v94
	v_exp_f32_e32 v95, v95
	v_exp_f32_e32 v96, v96
	s_waitcnt lgkmcnt(4)
	v_mfma_f32_32x32x16_bf16 v[18:33], v[182:185], v[6:9], v[18:33]
	ds_read_b64_tr_b16 v[182:183], v2 offset:29440
	ds_read_b64_tr_b16 v[184:185], v2 offset:30592
	v_exp_f32_e32 v97, v97
	v_exp_f32_e32 v98, v98
	v_exp_f32_e32 v99, v99
	v_exp_f32_e32 v100, v100
	v_exp_f32_e32 v101, v101
	v_exp_f32_e32 v102, v102
	v_mfma_f32_32x32x16_bf16 v[50:65], v[134:137], v[6:9], v[50:65]
	v_cvt_pk_bf16_f32 v6, v82, v83
	v_cvt_pk_bf16_f32 v7, v84, v85
	v_cvt_pk_bf16_f32 v8, v86, v87
	v_cvt_pk_bf16_f32 v9, v88, v89
	v_exp_f32_e32 v103, v103
	v_exp_f32_e32 v104, v104
	v_exp_f32_e32 v105, v105
	s_waitcnt lgkmcnt(4)
	v_mfma_f32_32x32x16_bf16 v[34:49], v[186:189], v[6:9], v[34:49]
	ds_read_b64_tr_b16 v[186:187], v2 offset:29504
	ds_read_b64_tr_b16 v[188:189], v2 offset:30656
	v_exp_f32_e32 v106, v106
	v_exp_f32_e32 v107, v107
	v_exp_f32_e32 v108, v108
	v_exp_f32_e32 v109, v109
	v_exp_f32_e32 v110, v110
	v_exp_f32_e32 v111, v111
	s_waitcnt lgkmcnt(4)
	v_mfma_f32_32x32x16_bf16 v[18:33], v[10:13], v[6:9], v[18:33]
	ds_read_b64_tr_b16 v[10:11], v2 offset:31744
	ds_read_b64_tr_b16 v[12:13], v2 offset:32896
	v_exp_f32_e32 v112, v112
	v_exp_f32_e32 v113, v113
	v_exp_f32_e32 v66, v66
	v_exp_f32_e32 v67, v67
	v_exp_f32_e32 v68, v68
	v_exp_f32_e32 v69, v69
	v_mfma_f32_32x32x16_bf16 v[50:65], v[134:137], v[6:9], v[50:65]
	v_cvt_pk_bf16_f32 v6, v90, v91
	v_cvt_pk_bf16_f32 v7, v92, v93
	v_cvt_pk_bf16_f32 v8, v94, v95
	v_cvt_pk_bf16_f32 v9, v96, v97
	v_exp_f32_e32 v70, v70
	v_exp_f32_e32 v71, v71
	v_exp_f32_e32 v72, v72
	s_waitcnt lgkmcnt(4)
	v_mfma_f32_32x32x16_bf16 v[34:49], v[182:185], v[6:9], v[34:49]
	ds_read_b64_tr_b16 v[182:183], v2 offset:31808
	ds_read_b64_tr_b16 v[184:185], v2 offset:32960
	v_exp_f32_e32 v73, v73
	v_exp_f32_e32 v74, v74
	v_exp_f32_e32 v75, v75
	v_exp_f32_e32 v76, v76
	v_exp_f32_e32 v77, v77
	v_exp_f32_e32 v78, v78
	s_waitcnt lgkmcnt(4)
	v_mfma_f32_32x32x16_bf16 v[18:33], v[186:189], v[6:9], v[18:33]
	ds_read_b64_tr_b16 v[186:187], v2 offset:34048
	ds_read_b64_tr_b16 v[188:189], v2 offset:35200
	v_exp_f32_e32 v79, v79
	v_exp_f32_e32 v80, v80
	v_exp_f32_e32 v81, v81
	s_mov_b64 s[72:73], 0
	v_mfma_f32_32x32x16_bf16 v[50:65], v[134:137], v[6:9], v[50:65]
	v_cvt_pk_bf16_f32 v6, v98, v99
	v_cvt_pk_bf16_f32 v7, v100, v101
	v_cvt_pk_bf16_f32 v8, v102, v103
	v_cvt_pk_bf16_f32 v9, v104, v105
	s_waitcnt lgkmcnt(4)
	s_nop 0
	v_mfma_f32_32x32x16_bf16 v[34:49], v[10:13], v[6:9], v[34:49]
	ds_read_b64_tr_b16 v[10:11], v2 offset:34112
	ds_read_b64_tr_b16 v[12:13], v2 offset:35264
	s_waitcnt lgkmcnt(4)
	v_mfma_f32_32x32x16_bf16 v[18:33], v[182:185], v[6:9], v[18:33]
	ds_read_b64_tr_b16 v[182:183], v2 offset:36352
	ds_read_b64_tr_b16 v[184:185], v2 offset:37504
	v_mfma_f32_32x32x16_bf16 v[50:65], v[134:137], v[6:9], v[50:65]
	v_cvt_pk_bf16_f32 v6, v106, v107
	v_cvt_pk_bf16_f32 v7, v108, v109
	v_cvt_pk_bf16_f32 v8, v110, v111
	v_cvt_pk_bf16_f32 v9, v112, v113
	s_waitcnt lgkmcnt(4)
	s_nop 0
	v_mfma_f32_32x32x16_bf16 v[34:49], v[186:189], v[6:9], v[34:49]
	ds_read_b64_tr_b16 v[186:187], v2 offset:36416
	ds_read_b64_tr_b16 v[188:189], v2 offset:37568
	s_waitcnt lgkmcnt(4)
	v_mfma_f32_32x32x16_bf16 v[18:33], v[10:13], v[6:9], v[18:33]
	ds_read_b64_tr_b16 v[10:11], v2 offset:38656
	ds_read_b64_tr_b16 v[12:13], v2 offset:39808
	v_mfma_f32_32x32x16_bf16 v[50:65], v[134:137], v[6:9], v[50:65]
	v_cvt_pk_bf16_f32 v6, v66, v67
	v_cvt_pk_bf16_f32 v7, v68, v69
	v_cvt_pk_bf16_f32 v8, v70, v71
	v_cvt_pk_bf16_f32 v9, v72, v73
	s_waitcnt lgkmcnt(4)
	s_nop 0
	v_mfma_f32_32x32x16_bf16 v[34:49], v[182:185], v[6:9], v[34:49]
	ds_read_b64_tr_b16 v[182:183], v2 offset:38720
	ds_read_b64_tr_b16 v[184:185], v2 offset:39872
	s_waitcnt lgkmcnt(4)
	v_mfma_f32_32x32x16_bf16 v[18:33], v[186:189], v[6:9], v[18:33]
	v_mfma_f32_32x32x16_bf16 v[50:65], v[134:137], v[6:9], v[50:65]
	v_cvt_pk_bf16_f32 v6, v74, v75
	v_cvt_pk_bf16_f32 v7, v76, v77
	v_cvt_pk_bf16_f32 v8, v78, v79
	v_cvt_pk_bf16_f32 v9, v80, v81
	s_waitcnt lgkmcnt(2)
	s_nop 0
	v_mfma_f32_32x32x16_bf16 v[34:49], v[10:13], v[6:9], v[34:49]
	s_waitcnt lgkmcnt(0)
	v_mfma_f32_32x32x16_bf16 v[18:33], v[182:185], v[6:9], v[18:33]
	v_mfma_f32_32x32x16_bf16 v[50:65], v[134:137], v[6:9], v[50:65]
